# norm2 ctx-row split-K reduce (S=11): partial+gate loads for 3 chunks hoisted, 4th chunk issued after chunk 0 (3 round trips instead of 9)
# speedup vs baseline: 1.0108x; 1.0006x over previous
; __device__ __forceinline__ void norm_phase(const float* xL, const float* xC, const float* gain, const float* modl  , int ishift, bf16_t* H, int nrows,
;                                            const float* part, int nsplit, const float* pgate  , float pscale, float* xCw) {
;     ...
;     if (nsplit > 0) for (int row = RL + gw; row < nrows; row += NGW) {
;         f32x4 v[4];
;         const float* xr = xC + (size_t)(row - RL) * DM;
; #pragma unroll
;         for (int j = 0; j < 4; ++j) v[j] = *(const f32x4*)(xr + 4 * lane + 256 * j);
; #pragma unroll
;         for (int j = 0; j < 4; ++j) {
;             f32x4 pv[11];
; #pragma unroll
;             for (int ks = 0; ks < 11; ++ks) if (ks < nsplit) pv[ks] = *(const f32x4*)(part + ((size_t)ks * RC + (row - RL)) * DM + 4 * lane + 256 * j);
;             f32x4 sum = {0.f, 0.f, 0.f, 0.f};
; #pragma unroll
;             for (int ks = 0; ks < 11; ++ks) if (ks < nsplit) sum += pv[ks];
;             v[j] += sum * (*(const f32x4*)(pgate + 4 * lane + 256 * j) * pscale);
;             *(f32x4*)(xCw + (size_t)(row - RL) * DM + 4 * lane + 256 * j) = v[j];
.LBB0_334:
	v_lshl_add_u64 v[54:55], s[96:97], 0, v[72:73]
	v_add_co_u32_e32 v32, vcc, 0x12000000, v54
	s_add_i32 s0, s0, s88
	s_nop 0
	v_addc_co_u32_e32 v33, vcc, 0, v55, vcc
	v_add_co_u32_e32 v34, vcc, 0x21b80000, v54
	global_load_dwordx4 v[20:23], v[32:33], off
	global_load_dwordx4 v[28:31], v[32:33], off offset:1024
	global_load_dwordx4 v[24:27], v[32:33], off offset:2048
	global_load_dwordx4 v[16:19], v[32:33], off offset:3072
	v_addc_co_u32_e32 v35, vcc, 0, v55, vcc
	v_add_co_u32_e32 v36, vcc, 0x21f80000, v54
	global_load_dwordx4 v[56:59], v[34:35], off
	s_nop 0
	v_addc_co_u32_e32 v37, vcc, 0, v55, vcc
	v_add_co_u32_e32 v38, vcc, 0x22380000, v54
	global_load_dwordx4 v[60:63], v[36:37], off
	s_nop 0
	v_addc_co_u32_e32 v39, vcc, 0, v55, vcc
	v_add_co_u32_e32 v40, vcc, 0x22780000, v54
	global_load_dwordx4 v[74:77], v[38:39], off
	s_nop 0
	v_addc_co_u32_e32 v41, vcc, 0, v55, vcc
	v_add_co_u32_e32 v42, vcc, 0x22b80000, v54
	global_load_dwordx4 v[78:81], v[40:41], off
	s_nop 0
	v_addc_co_u32_e32 v43, vcc, 0, v55, vcc
	v_add_co_u32_e32 v44, vcc, 0x22f80000, v54
	global_load_dwordx4 v[82:85], v[42:43], off
	s_nop 0
	v_addc_co_u32_e32 v45, vcc, 0, v55, vcc
	v_add_co_u32_e32 v46, vcc, 0x23380000, v54
	global_load_dwordx4 v[86:89], v[44:45], off
	s_nop 0
	v_addc_co_u32_e32 v47, vcc, 0, v55, vcc
	v_add_co_u32_e32 v48, vcc, 0x23780000, v54
	global_load_dwordx4 v[90:93], v[46:47], off
	s_nop 0
	v_addc_co_u32_e32 v49, vcc, 0, v55, vcc
	v_add_co_u32_e32 v50, vcc, 0x23b80000, v54
	global_load_dwordx4 v[94:97], v[48:49], off
	s_nop 0
	v_addc_co_u32_e32 v51, vcc, 0, v55, vcc
	v_add_co_u32_e32 v52, vcc, 0x23f80000, v54
	global_load_dwordx4 v[98:101], v[50:51], off
	s_nop 0
	v_addc_co_u32_e32 v53, vcc, 0, v55, vcc
	v_add_co_u32_e32 v54, vcc, 0x24380000, v54
	global_load_dwordx4 v[102:105], v[52:53], off
	s_nop 0
	v_addc_co_u32_e32 v55, vcc, 0, v55, vcc
	global_load_dwordx4 v[106:109], v[54:55], off
	global_load_dwordx4 v[216:219], v[64:65], off
	global_load_dwordx4 v[220:223], v[64:65], off offset:1024
	global_load_dwordx4 v[224:227], v[64:65], off offset:2048
	global_load_dwordx4 v[228:231], v[64:65], off offset:3072
	global_load_dwordx4 v[110:113], v[34:35], off offset:1024
	global_load_dwordx4 v[114:117], v[36:37], off offset:1024
	global_load_dwordx4 v[118:121], v[38:39], off offset:1024
	global_load_dwordx4 v[122:125], v[40:41], off offset:1024
	global_load_dwordx4 v[126:129], v[42:43], off offset:1024
	global_load_dwordx4 v[130:133], v[44:45], off offset:1024
	global_load_dwordx4 v[134:137], v[46:47], off offset:1024
	global_load_dwordx4 v[138:141], v[48:49], off offset:1024
	global_load_dwordx4 v[142:145], v[50:51], off offset:1024
	global_load_dwordx4 v[146:149], v[52:53], off offset:1024
	global_load_dwordx4 v[150:153], v[54:55], off offset:1024
	global_load_dwordx4 v[154:157], v[34:35], off offset:2048
	global_load_dwordx4 v[158:161], v[36:37], off offset:2048
	global_load_dwordx4 v[162:165], v[38:39], off offset:2048
	global_load_dwordx4 v[166:169], v[40:41], off offset:2048
	global_load_dwordx4 v[170:173], v[42:43], off offset:2048
	global_load_dwordx4 v[174:177], v[44:45], off offset:2048
	global_load_dwordx4 v[178:181], v[46:47], off offset:2048
	global_load_dwordx4 v[182:185], v[48:49], off offset:2048
	global_load_dwordx4 v[186:189], v[50:51], off offset:2048
	global_load_dwordx4 v[208:211], v[52:53], off offset:2048
	global_load_dwordx4 v[212:215], v[54:55], off offset:2048
	v_lshl_add_u64 v[72:73], v[72:73], 0, s[64:65]
	s_cmp_lt_i32 s0, 0x8400
	s_waitcnt vmcnt(36)
	v_add_f32_e32 v58, 0, v58
	v_add_f32_e32 v59, 0, v59
	v_add_f32_e32 v56, 0, v56
	v_add_f32_e32 v57, 0, v57
	s_waitcnt vmcnt(35)
	v_add_f32_e32 v58, v58, v62
	v_add_f32_e32 v59, v59, v63
	v_add_f32_e32 v56, v56, v60
	v_add_f32_e32 v57, v57, v61
	s_waitcnt vmcnt(34)
	v_add_f32_e32 v58, v58, v76
	v_add_f32_e32 v59, v59, v77
	v_add_f32_e32 v56, v56, v74
	v_add_f32_e32 v57, v57, v75
	s_waitcnt vmcnt(33)
	v_add_f32_e32 v58, v58, v80
	v_add_f32_e32 v59, v59, v81
	v_add_f32_e32 v56, v56, v78
	v_add_f32_e32 v57, v57, v79
	s_waitcnt vmcnt(32)
	v_add_f32_e32 v58, v58, v84
	v_add_f32_e32 v59, v59, v85
	v_add_f32_e32 v56, v56, v82
	v_add_f32_e32 v57, v57, v83
	s_waitcnt vmcnt(31)
	v_add_f32_e32 v58, v58, v88
	v_add_f32_e32 v59, v59, v89
	v_add_f32_e32 v56, v56, v86
	v_add_f32_e32 v57, v57, v87
	s_waitcnt vmcnt(30)
	v_add_f32_e32 v58, v58, v92
	v_add_f32_e32 v59, v59, v93
	v_add_f32_e32 v56, v56, v90
	v_add_f32_e32 v57, v57, v91
	s_waitcnt vmcnt(29)
	v_add_f32_e32 v58, v58, v96
	v_add_f32_e32 v59, v59, v97
	v_add_f32_e32 v56, v56, v94
	v_add_f32_e32 v57, v57, v95
	s_waitcnt vmcnt(28)
	v_add_f32_e32 v58, v58, v100
	v_add_f32_e32 v59, v59, v101
	v_add_f32_e32 v56, v56, v98
	v_add_f32_e32 v57, v57, v99
	s_waitcnt vmcnt(27)
	v_add_f32_e32 v58, v58, v104
	v_add_f32_e32 v59, v59, v105
	v_add_f32_e32 v56, v56, v102
	v_add_f32_e32 v57, v57, v103
	s_waitcnt vmcnt(26)
	v_add_f32_e32 v58, v58, v108
	v_add_f32_e32 v59, v59, v109
	v_add_f32_e32 v56, v56, v106
	v_add_f32_e32 v57, v57, v107
	s_waitcnt vmcnt(25)
	v_mul_f32_e32 v218, 0.5, v218
	v_mul_f32_e32 v219, 0.5, v219
	v_mul_f32_e32 v216, 0.5, v216
	v_mul_f32_e32 v217, 0.5, v217
	v_fma_f32 v22, v58, v218, v22
	v_fma_f32 v23, v59, v219, v23
	v_fma_f32 v20, v56, v216, v20
	v_fma_f32 v21, v57, v217, v21
	global_store_dwordx4 v[32:33], v[20:23], off
	global_load_dwordx4 v[56:59], v[34:35], off offset:3072
	global_load_dwordx4 v[60:63], v[36:37], off offset:3072
	global_load_dwordx4 v[74:77], v[38:39], off offset:3072
	global_load_dwordx4 v[78:81], v[40:41], off offset:3072
	global_load_dwordx4 v[82:85], v[42:43], off offset:3072
	global_load_dwordx4 v[86:89], v[44:45], off offset:3072
	global_load_dwordx4 v[90:93], v[46:47], off offset:3072
	global_load_dwordx4 v[94:97], v[48:49], off offset:3072
	global_load_dwordx4 v[98:101], v[50:51], off offset:3072
	global_load_dwordx4 v[102:105], v[52:53], off offset:3072
	global_load_dwordx4 v[106:109], v[54:55], off offset:3072
	s_waitcnt vmcnt(33)
; __device__ __forceinline__ void norm_phase(const float* xL, const float* xC, const float* gain, const float* modl  , int ishift, bf16_t* H, int nrows,
;                                            const float* part, int nsplit, const float* pgate  , float pscale, float* xCw) {
;     ...
; #pragma unroll
;         for (int j = 0; j < 4; ++j) {
;             f32x4 pv[11];
; #pragma unroll
;             for (int ks = 0; ks < 11; ++ks) if (ks < nsplit) pv[ks] = *(const f32x4*)(part + ((size_t)ks * RC + (row - RL)) * DM + 4 * lane + 256 * j);
;             f32x4 sum = {0.f, 0.f, 0.f, 0.f};
; #pragma unroll
;             for (int ks = 0; ks < 11; ++ks) if (ks < nsplit) sum += pv[ks];
;             v[j] += sum * (*(const f32x4*)(pgate + 4 * lane + 256 * j) * pscale);
;             *(f32x4*)(xCw + (size_t)(row - RL) * DM + 4 * lane + 256 * j) = v[j];
	v_add_f32_e32 v112, 0, v112
	v_add_f32_e32 v113, 0, v113
	v_add_f32_e32 v110, 0, v110
	v_add_f32_e32 v111, 0, v111
	s_waitcnt vmcnt(32)
	v_add_f32_e32 v112, v112, v116
	v_add_f32_e32 v113, v113, v117
	v_add_f32_e32 v110, v110, v114
	v_add_f32_e32 v111, v111, v115
	s_waitcnt vmcnt(31)
	v_add_f32_e32 v112, v112, v120
	v_add_f32_e32 v113, v113, v121
	v_add_f32_e32 v110, v110, v118
	v_add_f32_e32 v111, v111, v119
	s_waitcnt vmcnt(30)
	v_add_f32_e32 v112, v112, v124
	v_add_f32_e32 v113, v113, v125
	v_add_f32_e32 v110, v110, v122
	v_add_f32_e32 v111, v111, v123
	s_waitcnt vmcnt(29)
	v_add_f32_e32 v112, v112, v128
	v_add_f32_e32 v113, v113, v129
	v_add_f32_e32 v110, v110, v126
	v_add_f32_e32 v111, v111, v127
	s_waitcnt vmcnt(28)
	v_add_f32_e32 v112, v112, v132
	v_add_f32_e32 v113, v113, v133
	v_add_f32_e32 v110, v110, v130
	v_add_f32_e32 v111, v111, v131
	s_waitcnt vmcnt(27)
	v_add_f32_e32 v112, v112, v136
	v_add_f32_e32 v113, v113, v137
	v_add_f32_e32 v110, v110, v134
	v_add_f32_e32 v111, v111, v135
	s_waitcnt vmcnt(26)
	v_add_f32_e32 v112, v112, v140
	v_add_f32_e32 v113, v113, v141
	v_add_f32_e32 v110, v110, v138
	v_add_f32_e32 v111, v111, v139
	s_waitcnt vmcnt(25)
	v_add_f32_e32 v112, v112, v144
	v_add_f32_e32 v113, v113, v145
	v_add_f32_e32 v110, v110, v142
	v_add_f32_e32 v111, v111, v143
	s_waitcnt vmcnt(24)
	v_add_f32_e32 v112, v112, v148
	v_add_f32_e32 v113, v113, v149
	v_add_f32_e32 v110, v110, v146
	v_add_f32_e32 v111, v111, v147
	s_waitcnt vmcnt(23)
	v_add_f32_e32 v112, v112, v152
	v_add_f32_e32 v113, v113, v153
	v_add_f32_e32 v110, v110, v150
	v_add_f32_e32 v111, v111, v151
	v_mul_f32_e32 v222, 0.5, v222
	v_mul_f32_e32 v223, 0.5, v223
	v_mul_f32_e32 v220, 0.5, v220
	v_mul_f32_e32 v221, 0.5, v221
	v_fma_f32 v30, v112, v222, v30
	v_fma_f32 v31, v113, v223, v31
	v_fma_f32 v28, v110, v220, v28
	v_fma_f32 v29, v111, v221, v29
	global_store_dwordx4 v[32:33], v[28:31], off offset:1024
	s_waitcnt vmcnt(23)
	v_add_f32_e32 v156, 0, v156
	v_add_f32_e32 v157, 0, v157
	v_add_f32_e32 v154, 0, v154
	v_add_f32_e32 v155, 0, v155
	s_waitcnt vmcnt(22)
	v_add_f32_e32 v156, v156, v160
	v_add_f32_e32 v157, v157, v161
	v_add_f32_e32 v154, v154, v158
	v_add_f32_e32 v155, v155, v159
	s_waitcnt vmcnt(21)
	v_add_f32_e32 v156, v156, v164
	v_add_f32_e32 v157, v157, v165
	v_add_f32_e32 v154, v154, v162
	v_add_f32_e32 v155, v155, v163
	s_waitcnt vmcnt(20)
	v_add_f32_e32 v156, v156, v168
	v_add_f32_e32 v157, v157, v169
	v_add_f32_e32 v154, v154, v166
	v_add_f32_e32 v155, v155, v167
	s_waitcnt vmcnt(19)
	v_add_f32_e32 v156, v156, v172
	v_add_f32_e32 v157, v157, v173
	v_add_f32_e32 v154, v154, v170
	v_add_f32_e32 v155, v155, v171
	s_waitcnt vmcnt(18)
	v_add_f32_e32 v156, v156, v176
	v_add_f32_e32 v157, v157, v177
	v_add_f32_e32 v154, v154, v174
	v_add_f32_e32 v155, v155, v175
	s_waitcnt vmcnt(17)
	v_add_f32_e32 v156, v156, v180
	v_add_f32_e32 v157, v157, v181
	v_add_f32_e32 v154, v154, v178
	v_add_f32_e32 v155, v155, v179
	s_waitcnt vmcnt(16)
	v_add_f32_e32 v156, v156, v184
	v_add_f32_e32 v157, v157, v185
	v_add_f32_e32 v154, v154, v182
	v_add_f32_e32 v155, v155, v183
	s_waitcnt vmcnt(15)
	v_add_f32_e32 v156, v156, v188
	v_add_f32_e32 v157, v157, v189
	v_add_f32_e32 v154, v154, v186
	v_add_f32_e32 v155, v155, v187
	s_waitcnt vmcnt(14)
	v_add_f32_e32 v156, v156, v210
	v_add_f32_e32 v157, v157, v211
	v_add_f32_e32 v154, v154, v208
	v_add_f32_e32 v155, v155, v209
	s_waitcnt vmcnt(13)
	v_add_f32_e32 v156, v156, v214
	v_add_f32_e32 v157, v157, v215
	v_add_f32_e32 v154, v154, v212
	v_add_f32_e32 v155, v155, v213
	v_mul_f32_e32 v226, 0.5, v226
	v_mul_f32_e32 v227, 0.5, v227
	v_mul_f32_e32 v224, 0.5, v224
	v_mul_f32_e32 v225, 0.5, v225
	v_fma_f32 v26, v156, v226, v26
	v_fma_f32 v27, v157, v227, v27
	v_fma_f32 v24, v154, v224, v24
	v_fma_f32 v25, v155, v225, v25
	global_store_dwordx4 v[32:33], v[24:27], off offset:2048
	s_waitcnt vmcnt(12)
	v_add_f32_e32 v58, 0, v58
	v_add_f32_e32 v59, 0, v59
	v_add_f32_e32 v56, 0, v56
	v_add_f32_e32 v57, 0, v57
	s_waitcnt vmcnt(11)
	v_add_f32_e32 v58, v58, v62
	v_add_f32_e32 v59, v59, v63
	v_add_f32_e32 v56, v56, v60
	v_add_f32_e32 v57, v57, v61
	s_waitcnt vmcnt(10)
	v_add_f32_e32 v58, v58, v76
	v_add_f32_e32 v59, v59, v77
	v_add_f32_e32 v56, v56, v74
	v_add_f32_e32 v57, v57, v75
	s_waitcnt vmcnt(9)
	v_add_f32_e32 v58, v58, v80
	v_add_f32_e32 v59, v59, v81
	v_add_f32_e32 v56, v56, v78
	v_add_f32_e32 v57, v57, v79
	s_waitcnt vmcnt(8)
	v_add_f32_e32 v58, v58, v84
	v_add_f32_e32 v59, v59, v85
	v_add_f32_e32 v56, v56, v82
	v_add_f32_e32 v57, v57, v83
	s_waitcnt vmcnt(7)
	v_add_f32_e32 v58, v58, v88
	v_add_f32_e32 v59, v59, v89
	v_add_f32_e32 v56, v56, v86
	v_add_f32_e32 v57, v57, v87
	s_waitcnt vmcnt(6)
	v_add_f32_e32 v58, v58, v92
	v_add_f32_e32 v59, v59, v93
	v_add_f32_e32 v56, v56, v90
	v_add_f32_e32 v57, v57, v91
	s_waitcnt vmcnt(5)
	v_add_f32_e32 v58, v58, v96
	v_add_f32_e32 v59, v59, v97
	v_add_f32_e32 v56, v56, v94
	v_add_f32_e32 v57, v57, v95
	s_waitcnt vmcnt(4)
	v_add_f32_e32 v58, v58, v100
	v_add_f32_e32 v59, v59, v101
	v_add_f32_e32 v56, v56, v98
	v_add_f32_e32 v57, v57, v99
	s_waitcnt vmcnt(3)
; __device__ __forceinline__ unsigned cvt_pk_bf16(float lo, float hi) { const f32x2 v = {lo, hi}; const bf16x2_t b = __builtin_convertvector(v, bf16x2_t); return __builtin_bit_cast(unsigned, b); }
; __device__ __forceinline__ float wave_sum(float v) { return xadd32(sum32(v)); }
; __device__ __forceinline__ void norm_row(const f32x4 (&v)[4], const f32x4 (&gn)[4], const float* sh, bf16_t* hrow, int lane) {
;     const float* scl = sh + 1024;
;     f32x4 sv[4], cv[4];
; #pragma unroll
;     for (int j = 0; j < 4; ++j) { sv[j] = *(const f32x4*)(sh + 4 * lane + 256 * j); cv[j] = *(const f32x4*)(scl + 4 * lane + 256 * j); }
;     float ss = 0.f;
; #pragma unroll
;     for (int j = 0; j < 4; ++j) ss += (v[j][0] * v[j][0] + v[j][1] * v[j][1]) + (v[j][2] * v[j][2] + v[j][3] * v[j][3]);
;     const float rstd = __builtin_amdgcn_rsqf(wave_sum(ss) * (1.0f / DM) + EPS);
; #pragma unroll
;     for (int j = 0; j < 4; ++j) {
;         const f32x4 y = v[j] * rstd * gn[j] * (cv[j] + 1.0f) + sv[j];
;         u32x2 w; w.x = cvt_pk_bf16(y[0], y[1]); w.y = cvt_pk_bf16(y[2], y[3]);
;         *(u32x2*)(hrow + 4 * lane + 256 * j) = w;
;     }
; __device__ __forceinline__ void norm_phase(const float* xL, const float* xC, const float* gain, const float* modl  , int ishift, bf16_t* H, int nrows,
;                                            const float* part, int nsplit, const float* pgate  , float pscale, float* xCw) {
;     ...
;     if (nsplit > 0) for (int row = RL + gw; row < nrows; row += NGW) {
;         f32x4 v[4];
;         const float* xr = xC + (size_t)(row - RL) * DM;
; #pragma unroll
;         for (int j = 0; j < 4; ++j) v[j] = *(const f32x4*)(xr + 4 * lane + 256 * j);
; #pragma unroll
;         for (int j = 0; j < 4; ++j) {
;             f32x4 pv[11];
; #pragma unroll
;             for (int ks = 0; ks < 11; ++ks) if (ks < nsplit) pv[ks] = *(const f32x4*)(part + ((size_t)ks * RC + (row - RL)) * DM + 4 * lane + 256 * j);
;             f32x4 sum = {0.f, 0.f, 0.f, 0.f};
; #pragma unroll
;             for (int ks = 0; ks < 11; ++ks) if (ks < nsplit) sum += pv[ks];
;             v[j] += sum * (*(const f32x4*)(pgate + 4 * lane + 256 * j) * pscale);
;             *(f32x4*)(xCw + (size_t)(row - RL) * DM + 4 * lane + 256 * j) = v[j];
;         }
;         norm_row(v, gn, modl + (size_t)4 * 9216 + ishift * 1024, H + (size_t)row * DM, lane);
	v_add_f32_e32 v58, v58, v104
	v_add_f32_e32 v59, v59, v105
	v_add_f32_e32 v56, v56, v102
	v_add_f32_e32 v57, v57, v103
	s_waitcnt vmcnt(2)
	v_add_f32_e32 v58, v58, v108
	v_add_f32_e32 v59, v59, v109
	v_add_f32_e32 v56, v56, v106
	v_add_f32_e32 v57, v57, v107
	v_mul_f32_e32 v74, v21, v21
	v_mul_f32_e32 v75, v23, v23
	v_fmac_f32_e32 v74, v20, v20
	v_fmac_f32_e32 v75, v22, v22
	v_add_f32_e32 v74, v74, v75
	v_mul_f32_e32 v75, v29, v29
	v_mul_f32_e32 v76, v31, v31
	v_fmac_f32_e32 v75, v28, v28
	v_fmac_f32_e32 v76, v30, v30
	v_add_f32_e32 v75, v75, v76
	v_add_f32_e32 v74, v74, v75
	v_mul_f32_e32 v75, v25, v25
	v_mul_f32_e32 v76, v27, v27
	v_fmac_f32_e32 v75, v24, v24
	v_fmac_f32_e32 v76, v26, v26
	v_add_f32_e32 v75, v75, v76
	v_add_f32_e32 v74, v74, v75
	v_mul_f32_e32 v230, 0.5, v230
	v_mul_f32_e32 v231, 0.5, v231
	v_mul_f32_e32 v228, 0.5, v228
	v_mul_f32_e32 v229, 0.5, v229
	v_fma_f32 v18, v58, v230, v18
	v_fma_f32 v19, v59, v231, v19
	v_fma_f32 v16, v56, v228, v16
	v_fma_f32 v17, v57, v229, v17
	global_store_dwordx4 v[32:33], v[16:19], off offset:3072
	global_load_dwordx4 v[56:59], v[66:67], off
	global_load_dwordx4 v[60:63], v[68:69], off
	global_load_dwordx4 v[48:51], v[66:67], off offset:1024
	global_load_dwordx4 v[52:55], v[68:69], off offset:1024
	global_load_dwordx4 v[40:43], v[66:67], off offset:2048
	global_load_dwordx4 v[44:47], v[68:69], off offset:2048
	global_load_dwordx4 v[32:35], v[66:67], off offset:3072
	global_load_dwordx4 v[36:39], v[68:69], off offset:3072
	v_mul_f32_e32 v75, v17, v17
	v_mul_f32_e32 v76, v19, v19
	v_fmac_f32_e32 v75, v16, v16
	v_fmac_f32_e32 v76, v18, v18
	v_add_f32_e32 v75, v75, v76
	v_add_f32_e32 v74, v74, v75
	ds_swizzle_b32 v75, v74 offset:swizzle(SWAP,1)
	v_lshl_add_u64 v[76:77], s[96:97], 0, v[70:71]
	v_lshl_add_u64 v[70:71], v[70:71], 0, s[92:93]
	s_waitcnt lgkmcnt(0)
	v_add_f32_e32 v74, v74, v75
	ds_swizzle_b32 v75, v74 offset:swizzle(SWAP,2)
	s_waitcnt lgkmcnt(0)
	v_add_f32_e32 v74, v74, v75
	ds_swizzle_b32 v75, v74 offset:swizzle(SWAP,4)
	s_waitcnt lgkmcnt(0)
	v_add_f32_e32 v74, v74, v75
	ds_swizzle_b32 v75, v74 offset:swizzle(SWAP,8)
	s_waitcnt lgkmcnt(0)
	v_add_f32_e32 v74, v74, v75
	ds_swizzle_b32 v75, v74 offset:swizzle(SWAP,16)
	s_waitcnt lgkmcnt(0)
	v_add_f32_e32 v74, v74, v75
	v_mov_b32_e32 v75, v74
	s_nop 1
	v_permlane32_swap_b32_e32 v74, v75
	v_add_f32_e32 v74, v74, v75
	v_fmamk_f32 v74, v74, 0x3a800000, v193
	v_rsq_f32_e32 v74, v74
	s_waitcnt vmcnt(6)
	v_add_f32_e32 v62, 1.0, v62
	v_add_f32_e32 v63, 1.0, v63
	v_mul_f32_e32 v22, v22, v74
	v_mul_f32_e32 v23, v23, v74
	v_mul_f32_e32 v20, v20, v74
	v_mul_f32_e32 v21, v21, v74
	v_mul_f32_e32 v22, v2, v22
	v_mul_f32_e32 v23, v3, v23
	v_mul_f32_e32 v20, v0, v20
	v_mul_f32_e32 v21, v1, v21
	v_add_f32_e32 v60, 1.0, v60
	v_add_f32_e32 v61, 1.0, v61
	v_fma_f32 v22, v62, v22, v58
	v_fma_f32 v23, v63, v23, v59
	v_fma_f32 v20, v60, v20, v56
	v_fma_f32 v21, v61, v21, v57
	v_mul_f32_e32 v28, v28, v74
	v_mul_f32_e32 v29, v29, v74
	v_cvt_pk_bf16_f32 v20, v20, v21
	v_cvt_pk_bf16_f32 v21, v22, v23
	v_add_co_u32_e32 v22, vcc, s47, v76
	v_mul_f32_e32 v28, v4, v28
	v_mul_f32_e32 v29, v5, v29
	s_nop 0
	v_addc_co_u32_e32 v23, vcc, 0, v77, vcc
	global_store_dwordx2 v[22:23], v[20:21], off
	v_mul_f32_e32 v20, v30, v74
	v_mul_f32_e32 v21, v31, v74
	s_waitcnt vmcnt(5)
	v_add_f32_e32 v30, 1.0, v54
	v_add_f32_e32 v31, 1.0, v55
	v_mul_f32_e32 v20, v6, v20
	v_mul_f32_e32 v21, v7, v21
	v_add_f32_e32 v52, 1.0, v52
	v_add_f32_e32 v53, 1.0, v53
	v_fma_f32 v20, v30, v20, v50
	v_fma_f32 v21, v31, v21, v51
	v_fma_f32 v28, v52, v28, v48
	v_fma_f32 v29, v53, v29, v49
	v_mul_f32_e32 v24, v24, v74
	v_mul_f32_e32 v25, v25, v74
	v_cvt_pk_bf16_f32 v28, v28, v29
	v_cvt_pk_bf16_f32 v29, v20, v21
	v_mul_f32_e32 v20, v26, v74
	v_mul_f32_e32 v21, v27, v74
	global_store_dwordx2 v[22:23], v[28:29], off offset:512
	v_mul_f32_e32 v24, v8, v24
	v_mul_f32_e32 v25, v9, v25
	v_mul_f32_e32 v20, v10, v20
	v_mul_f32_e32 v21, v11, v21
	s_waitcnt vmcnt(4)
	v_add_f32_e32 v26, 1.0, v46
	v_add_f32_e32 v27, 1.0, v47
	v_add_f32_e32 v28, 1.0, v44
	v_add_f32_e32 v29, 1.0, v45
	v_fma_f32 v20, v26, v20, v42
	v_fma_f32 v21, v27, v21, v43
	v_fma_f32 v24, v28, v24, v40
	v_fma_f32 v25, v29, v25, v41
	v_mul_f32_e32 v18, v18, v74
	v_mul_f32_e32 v19, v19, v74
	v_cvt_pk_bf16_f32 v24, v24, v25
	v_cvt_pk_bf16_f32 v25, v20, v21
	v_mul_f32_e32 v16, v16, v74
	v_mul_f32_e32 v17, v17, v74
	global_store_dwordx2 v[22:23], v[24:25], off offset:1024
	v_mul_f32_e32 v16, v12, v16
	v_mul_f32_e32 v17, v13, v17
	v_mul_f32_e32 v18, v14, v18
	v_mul_f32_e32 v19, v15, v19
	s_waitcnt vmcnt(3)
	v_add_f32_e32 v20, 1.0, v38
	v_add_f32_e32 v21, 1.0, v39
	v_add_f32_e32 v24, 1.0, v36
	v_add_f32_e32 v25, 1.0, v37
	v_fma_f32 v18, v20, v18, v34
	v_fma_f32 v19, v21, v19, v35
	v_fma_f32 v16, v24, v16, v32
	v_fma_f32 v17, v25, v17, v33
	s_nop 0
	v_cvt_pk_bf16_f32 v16, v16, v17
	v_cvt_pk_bf16_f32 v17, v18, v19
	global_store_dwordx2 v[22:23], v[16:17], off offset:1536
	s_cbranch_scc1 .LBB0_334
